# v39 + helper WGs: 7168 P0-list tiles in P1 idle window and 7168 down2 tiles in P8 idle window, private loop copies with counted vmcnt waits and batched LDS reads
# baseline (speedup 1.0000x reference)
; #define LAS __attribute__((address_space(3)))
; #define REFRESH_IDS() do { lane = fresh_lane(); tid = wave * 64 + lane; } while (0)
; __global__ void __launch_bounds__(NWAVES * 64, 2) fwd(Args args) {
;     ...
;     if (IN(0)) {
;         REFRESH_IDS();
;         LAS float* scr = (LAS float*)(L + wave * (64 * 65 * 4));
;         const int NS0 = ((NI0 / 32 * 27) / NGW) * NGW;
;         P0_RUN(gw, NS0, NGW);
.LBB0_8:
	s_or_b64 exec, exec, s[4:5]
	s_lshl_b32 s4, s75, 3
	s_add_i32 s16, s4, s28
	s_lshl_b32 s18, s33, 3
	s_add_u32 s6, s14, 0x40000
	s_addc_u32 s7, s15, 0
	s_add_u32 s36, s14, 0x400000
	s_addc_u32 s37, s15, 0
	s_add_u32 s34, s14, 0xb400000
	s_addc_u32 s35, s15, 0
	s_load_dwordx2 s[96:97], s[0:1], 0x98
	s_add_u32 s10, s14, 0x10c00000
	s_addc_u32 s11, s15, 0
	s_add_u32 s26, s14, 0x2a800000
	s_addc_u32 s27, s15, 0
	s_waitcnt lgkmcnt(0)
	s_cmp_lt_i32 s96, 1
	s_cselect_b64 s[4:5], -1, 0
	s_cmp_gt_i32 s97, 0
	s_cselect_b64 s[20:21], -1, 0
	s_and_b64 s[4:5], s[4:5], s[20:21]
	s_and_b64 vcc, exec, s[4:5]
	s_mul_i32 s74, s28, 0x4100
	s_cbranch_vccz .LBB0_219
	s_abs_i32 s4, s18
	v_cvt_f32_u32_e32 v0, s4
	s_sub_i32 s5, 0, s4
	s_add_i32 s19, s74, 0
	v_mbcnt_lo_u32_b32 v140, -1, 0
	v_mbcnt_hi_u32_b32 v140, -1, v140
	v_rcp_iflag_f32_e32 v0, v0
	s_nop 0
	v_mul_f32_e32 v0, 0x4f7ffffe, v0
	v_cvt_u32_f32_e32 v0, v0
	s_nop 0
	v_readfirstlane_b32 s17, v0
	s_mul_i32 s5, s5, s17
	s_mul_hi_u32 s5, s17, s5
	s_add_i32 s17, s17, s5
	s_mul_hi_u32 s5, s17, 0x804e
	s_mul_i32 s5, s5, s4
	s_sub_i32 s5, 0x804e, s5
	s_sub_i32 s17, s5, s4
	s_cmp_ge_u32 s5, s4
	s_cselect_b32 s5, s17, s5
	s_sub_i32 s17, s5, s4
	s_cmp_ge_u32 s5, s4
	s_cselect_b32 s23, s17, s5
	s_sub_i32 s22, 0x804e, s23
	s_cmp_ge_i32 s16, s22
	s_cbranch_scc1 .LBB0_84
	s_cmpk_gt_i32 s16, 0x55ff
	s_cbranch_scc0 .LBB0_14
	s_cmpk_gt_u32 s16, 0x80ff
	s_cbranch_scc0 .LBB0_15
	s_add_u32 s42, s0, 48
	s_addc_u32 s43, s1, 0
	s_add_i32 s17, s16, 0x7f00
	s_and_b32 s20, s17, 0xffff
	s_mul_i32 s20, s20, 0x91a3
	s_load_dwordx2 s[4:5], s[0:1], 0x28
	s_lshr_b32 s20, s20, 23
	s_lshl_b32 s30, s20, 6
	s_mulk_i32 s20, 0xe1
	s_sub_i32 s17, s17, s20
	s_lshl_b32 s17, s17, 6
	s_and_b32 s17, s17, 0xffc0
	s_cbranch_execz .LBB0_16
	s_movk_i32 s25, 0x1040
	s_movk_i32 s24, 0x3820
	s_mov_b64 s[40:41], s[10:11]
	s_branch .LBB0_17

; #define LDS_BAR() do { asm volatile("s_waitcnt lgkmcnt(0)" ::: "memory"); __builtin_amdgcn_s_barrier(); asm volatile("" ::: "memory"); } while (0)
; #define LAS __attribute__((address_space(3)))
; #define REFRESH_IDS() do { lane = fresh_lane(); tid = wave * 64 + lane; } while (0)
; __global__ void __launch_bounds__(NWAVES * 64, 2) fwd(Args args) {
;     ...
;           for (unsigned it = 0u;; ++it) {
;               LDS_BAR();
;               const unsigned q = MISC[16 + (it & 1u)]; if (q >= NTB) break;
;               if (tid == 0) { int z = 0; asm volatile("" : "+v"(z)); qpre = __hip_atomic_fetch_add(ctl + CW_AQ + 64 + z, 1u, __ATOMIC_RELAXED, __HIP_MEMORY_SCOPE_AGENT); }
;               volatile LAS unsigned* qslot = MISC + 16 + ((it + 1u) & 1u);
;               REFRESH_IDS();
;               int t0 = NS0 + (int)q * 16 + wave, t1 = t0 + 8; t0 = t0 < NI0 - 1 ? t0 : NI0 - 1; t1 = t1 < NI0 - 1 ? t1 : NI0 - 1;
;               f32x4 va[16], vb[16]; P0T_DECL(a); P0T_DECL(b);
;               P0T_RESOLVE(a, t0); p0_load(aW, aN, ak0, an0, lane, va);
.LBB0_103:
	s_or_b64 exec, exec, s[46:47]
	s_lshl_b32 s23, s23, 4
	s_add_i32 s23, s20, s23
	s_min_i32 s24, s23, 0x9d3f
	s_cmpk_gt_u32 s23, 0x55ff
	v_mbcnt_lo_u32_b32 v140, -1, 0
	v_mbcnt_hi_u32_b32 v140, -1, v140
	s_cbranch_scc0 .LBB0_108
	s_cmpk_gt_u32 s23, 0x80ff
	s_mov_b64 s[46:47], -1
	s_cbranch_scc0 .LBB0_106
	s_add_i32 s25, s24, 0xffff7f00
	s_mul_hi_u32 s29, s25, 0x91a2b3c5
	s_lshr_b32 s29, s29, 7
	s_lshl_b32 s56, s29, 6
	s_mulk_i32 s29, 0xe1
	s_sub_i32 s25, s25, s29
	s_lshl_b32 s67, s25, 6
	s_mov_b64 s[46:47], 0
	s_mov_b64 s[60:61], s[40:41]

; __device__ __forceinline__ void p0_load(const float* W, int N, int k0, int n0, int lane, f32x4 (&v)[16]) {
;     const int c = lane & 15, rq = lane >> 4;
;     int col = n0 + 4 * c; col = col < N - 4 ? col : N - 4;
;     const float* p = W + (size_t)(k0 + rq) * N + col;
; #pragma unroll
;     for (int j = 0; j < 16; ++j) v[j] = __builtin_nontemporal_load((const f32x4*)(p + (size_t)(4 * j) * N));
; }
; __global__ void __launch_bounds__(NWAVES * 64, 2) fwd(Args args) {
;     ...
;               int t0 = NS0 + (int)q * 16 + wave, t1 = t0 + 8; t0 = t0 < NI0 - 1 ? t0 : NI0 - 1; t1 = t1 < NI0 - 1 ? t1 : NI0 - 1;
;               f32x4 va[16], vb[16]; P0T_DECL(a); P0T_DECL(b);
;               P0T_RESOLVE(a, t0); p0_load(aW, aN, ak0, an0, lane, va);
;               P0T_RESOLVE(b, t1); p0_load(bW, bN, bk0, bn0, lane, vb);
.LBB0_112:
	v_ashrrev_i32_e32 v142, 4, v140
	s_load_dwordx2 s[24:25], s[46:47], 0x0
	v_add_u32_e32 v1, s56, v142
	v_lshlrev_b32_e32 v0, 2, v140
	v_mad_u64_u32 v[2:3], s[46:47], v1, s68, 0
	v_and_b32_e32 v143, 60, v0
	v_ashrrev_i32_e32 v5, 31, v1
	v_mov_b32_e32 v4, v3
	v_or_b32_e32 v0, s67, v143
	s_add_i32 s29, s68, -4
	v_mad_u64_u32 v[4:5], s[46:47], v5, s68, v[4:5]
	v_min_i32_e32 v0, s29, v0
	v_mov_b32_e32 v3, v4
	s_waitcnt lgkmcnt(0)
	v_lshl_add_u64 v[2:3], v[2:3], 2, s[24:25]
	v_ashrrev_i32_e32 v1, 31, v0
	v_lshl_add_u64 v[0:1], v[0:1], 2, v[2:3]
	s_lshl_b32 s44, s68, 2
	v_lshl_add_u64 v[2:3], s[44:45], 2, v[0:1]
	s_lshl_b32 s44, s68, 3
	global_load_dwordx4 v[76:79], v[0:1], off nt
	global_load_dwordx4 v[72:75], v[2:3], off nt
	v_lshl_add_u64 v[2:3], s[44:45], 2, v[0:1]
	s_mul_i32 s44, s68, 12
	v_lshl_add_u64 v[4:5], s[44:45], 2, v[0:1]
	s_lshl_b32 s44, s68, 4
	global_load_dwordx4 v[84:87], v[2:3], off nt
	global_load_dwordx4 v[80:83], v[4:5], off nt
	v_lshl_add_u64 v[2:3], s[44:45], 2, v[0:1]
	s_mul_i32 s44, s68, 20
	v_lshl_add_u64 v[4:5], s[44:45], 2, v[0:1]
	s_mul_i32 s44, s68, 24
	global_load_dwordx4 v[92:95], v[2:3], off nt
	global_load_dwordx4 v[88:91], v[4:5], off nt
	v_lshl_add_u64 v[2:3], s[44:45], 2, v[0:1]
	s_mul_i32 s44, s68, 28
	v_lshl_add_u64 v[4:5], s[44:45], 2, v[0:1]
	s_lshl_b32 s44, s68, 5
	global_load_dwordx4 v[100:103], v[2:3], off nt
	global_load_dwordx4 v[96:99], v[4:5], off nt
	v_lshl_add_u64 v[2:3], s[44:45], 2, v[0:1]
	s_mul_i32 s44, s68, 36
	v_lshl_add_u64 v[4:5], s[44:45], 2, v[0:1]
	s_mul_i32 s44, s68, 40
	global_load_dwordx4 v[108:111], v[2:3], off nt
	global_load_dwordx4 v[104:107], v[4:5], off nt
	v_lshl_add_u64 v[2:3], s[44:45], 2, v[0:1]
	s_mul_i32 s44, s68, 44
	v_lshl_add_u64 v[4:5], s[44:45], 2, v[0:1]
	s_mul_i32 s44, s68, 48
	global_load_dwordx4 v[116:119], v[2:3], off nt
	global_load_dwordx4 v[112:115], v[4:5], off nt
	v_lshl_add_u64 v[2:3], s[44:45], 2, v[0:1]
	s_mul_i32 s44, s68, 52
	v_lshl_add_u64 v[4:5], s[44:45], 2, v[0:1]
	s_mul_i32 s44, s68, 56
	global_load_dwordx4 v[124:127], v[2:3], off nt
	global_load_dwordx4 v[120:123], v[4:5], off nt
	v_lshl_add_u64 v[2:3], s[44:45], 2, v[0:1]
	s_mul_i32 s44, s68, 60
	v_lshl_add_u64 v[0:1], s[44:45], 2, v[0:1]
	global_load_dwordx4 v[132:135], v[2:3], off nt
	global_load_dwordx4 v[128:131], v[0:1], off nt
	s_min_i32 s25, s23, 0x9d37
	s_cmpk_gt_u32 s23, 0x55f7
	s_cbranch_scc0 .LBB0_117
	s_cmpk_gt_u32 s23, 0x80f7
	s_mov_b64 s[46:47], -1
	s_cbranch_scc0 .LBB0_115
	s_add_i32 s23, s25, 0xffff7f08
	s_mul_hi_u32 s24, s23, 0x91a2b3c5
	s_lshr_b32 s24, s24, 7
	s_lshl_b32 s50, s24, 6
	s_mulk_i32 s24, 0xe1
	s_sub_i32 s23, s23, s24
	s_lshl_b32 s23, s23, 6
	s_mov_b64 s[46:47], 0
	s_mov_b64 s[54:55], s[40:41]

; #define LAS __attribute__((address_space(3)))
; #define REFRESH_IDS() do { lane = fresh_lane(); tid = wave * 64 + lane; } while (0)
; #define GRID_BAR() xcd_barrier(bar)
; #define GRID_BAR() do { } while (0)
; #define BOTH(k) (IN(k) && IN((k) + 1))
; __global__ void __launch_bounds__(NWAVES * 64, 2) fwd(Args args) {
;     ...
;     if (IN(0)) {
;         REFRESH_IDS();
;         LAS float* scr = (LAS float*)(L + wave * (64 * 65 * 4));
;         const int NS0 = ((NI0 / 32 * 27) / NGW) * NGW;
;         P0_RUN(gw, NS0, NGW);
;     ...
;     if (IN(1)) {
;         REFRESH_IDS();
;         pg8::Gemm g{XB, Wgu1, M, 2 * FF, D, LDD, LDD}; pg8::StaticOrder S; S.init(M, 2 * FF, G, bx);
;         pg8::EpiGateUp E{ACT, ssq};
;         pg8::gemm_phase<pg8::EpiGateUp, pg8::StaticOrder, true, true>(L, g, S, E, wave);
;         if (BOTH(1)) GRID_BAR();
.LBB0_240:
	s_cmpk_lt_u32 s8, 0xc0
	s_cbranch_scc1 .Lha_done
	v_writelane_b32 v238, s0, 0
	v_writelane_b32 v238, s1, 1
	v_writelane_b32 v238, s2, 2
	v_writelane_b32 v238, s3, 3
	v_writelane_b32 v238, s4, 4
	v_writelane_b32 v238, s5, 5
	v_writelane_b32 v238, s6, 6
	v_writelane_b32 v238, s7, 7
	v_writelane_b32 v238, s8, 8
	v_writelane_b32 v238, s9, 9
	v_writelane_b32 v238, s10, 10
	v_writelane_b32 v238, s11, 11
	v_writelane_b32 v238, s12, 12
	v_writelane_b32 v238, s13, 13
	v_writelane_b32 v238, s14, 14
	v_writelane_b32 v238, s15, 15
	v_writelane_b32 v238, s16, 16
	v_writelane_b32 v238, s17, 17
	v_writelane_b32 v238, s18, 18
	v_writelane_b32 v238, s19, 19
	v_writelane_b32 v238, s20, 20
	v_writelane_b32 v238, s21, 21
	v_writelane_b32 v238, s22, 22
	v_writelane_b32 v238, s23, 23
	v_writelane_b32 v238, s24, 24
	v_writelane_b32 v238, s25, 25
	v_writelane_b32 v238, s26, 26
	v_writelane_b32 v238, s27, 27
	v_writelane_b32 v238, s28, 28
	v_writelane_b32 v238, s29, 29
	v_writelane_b32 v238, s30, 30
	v_writelane_b32 v238, s31, 31
	v_writelane_b32 v238, s32, 32
	v_writelane_b32 v238, s33, 33
	v_writelane_b32 v238, s34, 34
	v_writelane_b32 v238, s35, 35
	v_writelane_b32 v238, s36, 36
	v_writelane_b32 v238, s37, 37
	v_writelane_b32 v238, s38, 38
	v_writelane_b32 v238, s39, 39
	v_writelane_b32 v238, s40, 40
	v_writelane_b32 v238, s41, 41
	v_writelane_b32 v238, s42, 42
	v_writelane_b32 v238, s43, 43
	v_writelane_b32 v238, s44, 44
	v_writelane_b32 v238, s45, 45
	v_writelane_b32 v238, s46, 46
	v_writelane_b32 v238, s47, 47
	v_writelane_b32 v238, s48, 48
	v_writelane_b32 v238, s49, 49
	v_writelane_b32 v238, s50, 50
	v_writelane_b32 v238, s51, 51
	v_writelane_b32 v238, s52, 52
	v_writelane_b32 v238, s53, 53
	v_writelane_b32 v238, s54, 54
	v_writelane_b32 v238, s55, 55
	v_writelane_b32 v238, s56, 56
	v_writelane_b32 v238, s57, 57
	v_writelane_b32 v238, s58, 58
	v_writelane_b32 v238, s59, 59
	v_writelane_b32 v238, s60, 60
	v_writelane_b32 v238, s61, 61
	v_writelane_b32 v238, s62, 62
	v_writelane_b32 v238, s63, 63
	v_writelane_b32 v239, s64, 0
	v_writelane_b32 v239, s65, 1
	v_writelane_b32 v239, s66, 2
	v_writelane_b32 v239, s67, 3
	v_writelane_b32 v239, s68, 4
	v_writelane_b32 v239, s69, 5
	v_writelane_b32 v239, s70, 6
	v_writelane_b32 v239, s71, 7
	v_writelane_b32 v239, s72, 8
	v_writelane_b32 v239, s73, 9
	v_writelane_b32 v239, s74, 10
	v_writelane_b32 v239, s75, 11
	v_writelane_b32 v239, s76, 12
	v_writelane_b32 v239, s77, 13
	v_writelane_b32 v239, s78, 14
	v_writelane_b32 v239, s79, 15
	v_writelane_b32 v239, s80, 16
	v_writelane_b32 v239, s81, 17
	v_writelane_b32 v239, s82, 18
	v_writelane_b32 v239, s83, 19
	v_writelane_b32 v239, s84, 20
	v_writelane_b32 v239, s85, 21
	v_writelane_b32 v239, s86, 22
	v_writelane_b32 v239, s87, 23
	v_writelane_b32 v239, s88, 24
	v_writelane_b32 v239, s89, 25
	v_writelane_b32 v239, s90, 26
	v_writelane_b32 v239, s91, 27
	v_writelane_b32 v239, s92, 28
	v_writelane_b32 v239, s93, 29
	v_writelane_b32 v239, s94, 30
	v_writelane_b32 v239, s95, 31
	v_writelane_b32 v239, s96, 32
	v_writelane_b32 v239, s97, 33
	v_writelane_b32 v239, s98, 34
	v_writelane_b32 v239, s99, 35
	v_writelane_b32 v239, s100, 36
	v_writelane_b32 v239, s101, 37
	v_writelane_b32 v239, vcc_lo, 38
	v_writelane_b32 v239, vcc_hi, 39
	v_writelane_b32 v239, m0, 40
	s_add_i32 s75, s8, 0xffffff40
	s_mov_b32 s33, 64
	s_lshl_b32 s9, s28, 6
	s_lshl_b32 s4, s75, 3
	s_add_i32 s16, s4, s28
	s_lshl_b32 s18, s33, 3
	s_add_u32 s6, s14, 0x40000
	s_addc_u32 s7, s15, 0
	s_add_u32 s36, s14, 0x400000
	s_addc_u32 s37, s15, 0
	s_add_u32 s34, s14, 0xb400000
	s_addc_u32 s35, s15, 0
	s_load_dwordx2 s[96:97], s[0:1], 0x98
	s_add_u32 s10, s14, 0x10c00000
	s_addc_u32 s11, s15, 0
	s_add_u32 s26, s14, 0x2a800000
	s_addc_u32 s27, s15, 0
	s_waitcnt lgkmcnt(0)
	s_cmp_lt_i32 s96, 1
	s_cselect_b64 s[4:5], -1, 0
	s_cmp_gt_i32 s97, 0
	s_cselect_b64 s[20:21], -1, 0
	s_and_b64 s[4:5], s[4:5], s[20:21]
	s_and_b64 vcc, exec, s[4:5]
	s_mul_i32 s74, s28, 0x4100
	s_cbranch_vccz .Lha_end
	s_abs_i32 s4, s18
	v_cvt_f32_u32_e32 v0, s4
	s_sub_i32 s5, 0, s4
	s_add_i32 s19, s74, 0
	v_mbcnt_lo_u32_b32 v140, -1, 0
	v_mbcnt_hi_u32_b32 v140, -1, v140
	v_rcp_iflag_f32_e32 v0, v0
	s_nop 0
	v_mul_f32_e32 v0, 0x4f7ffffe, v0
	v_cvt_u32_f32_e32 v0, v0
	s_nop 0
	v_readfirstlane_b32 s17, v0
	s_mul_i32 s5, s5, s17
	s_mul_hi_u32 s5, s17, s5
	s_add_i32 s17, s17, s5
	s_mul_hi_u32 s5, s17, 0x9c4e
	s_mul_i32 s5, s5, s4
	s_sub_i32 s5, 0x9c4e, s5
	s_sub_i32 s17, s5, s4
	s_cmp_ge_u32 s5, s4
	s_cselect_b32 s5, s17, s5
	s_sub_i32 s17, s5, s4
	s_cmp_ge_u32 s5, s4
	s_cselect_b32 s23, s17, s5
	s_sub_i32 s22, 0x9c4e, s23
	s_add_i32 s16, s16, 0x9d40
	s_mov_b32 s22, 0xb940
	s_cmp_ge_i32 s16, s22
	s_cbranch_scc1 .Lha_end
	s_cmpk_gt_i32 s16, 0x55ff
	s_cbranch_scc0 .Lha_14
	s_cmpk_gt_u32 s16, 0x80ff
	s_cbranch_scc0 .Lha_15
	s_add_u32 s42, s0, 48
	s_addc_u32 s43, s1, 0
	s_add_i32 s17, s16, 0x7f00
	s_and_b32 s20, s17, 0xffff
	s_mul_i32 s20, s20, 0x91a3
	s_load_dwordx2 s[4:5], s[0:1], 0x28
	s_lshr_b32 s20, s20, 23
	s_lshl_b32 s30, s20, 6
	s_mulk_i32 s20, 0xe1
	s_sub_i32 s17, s17, s20
	s_lshl_b32 s17, s17, 6
	s_and_b32 s17, s17, 0xffc0
	s_cbranch_execz .Lha_16
	s_movk_i32 s25, 0x1040
	s_movk_i32 s24, 0x3820
	s_mov_b64 s[40:41], s[10:11]
	s_branch .Lha_17

; #define LAS __attribute__((address_space(3)))
; __device__ __forceinline__ unsigned pk2(float lo, float hi) { return pg8::cvt_pk_bf16(lo, hi); }
; __device__ __forceinline__ void p0_finish(bf16* WT, const float* gain, int N, int k0, int n0, int ldw, int blk, int off, int lane, const f32x4 (&v)[16], LAS float* scr) {
;     const int c = lane & 15, rq = lane >> 4, c8 = lane & 7;
;     f32x4 g0 = {1.f, 1.f, 1.f, 1.f}, g1 = g0;
;     if (gain) { g0 = *(const f32x4*)(gain + k0 + 8 * c8); g1 = *(const f32x4*)(gain + k0 + 8 * c8 + 4); }
; #pragma unroll
;     for (int j = 0; j < 16; ++j) { LAS float* s = scr + (4 * j + rq) * 65 + 4 * c; s[0] = v[j][0]; s[1] = v[j][1]; s[2] = v[j][2]; s[3] = v[j][3]; }
;     asm volatile("s_waitcnt lgkmcnt(0)" ::: "memory");
; #pragma unroll
;     for (int jj = 0; jj < 8; ++jj) { const int n = (lane >> 3) + 8 * jj; const LAS float* s = scr + (8 * c8) * 65 + n;
;         u32x4 o; o.x = pk2(s[0 * 65] * g0[0], s[1 * 65] * g0[1]); o.y = pk2(s[2 * 65] * g0[2], s[3 * 65] * g0[3]); o.z = pk2(s[4 * 65] * g1[0], s[5 * 65] * g1[1]); o.w = pk2(s[6 * 65] * g1[2], s[7 * 65] * g1[3]);
;         const int ng = n0 + n;
;         if (ng < N) { const int row = (ng >> 7) * blk + (ng & 127) + off; __builtin_nontemporal_store(o, (u32x4*)(WT + (size_t)row * ldw + k0 + 8 * c8)); } }
.Lha_p0w_a1:
	ds_write2_b32 v156, v28, v29 offset1:1
	ds_write2_b32 v156, v30, v31 offset0:2 offset1:3
	ds_write2_b32 v159, v24, v25 offset1:1
	ds_write2_b32 v160, v26, v27 offset1:1
	ds_write2_b32 v161, v36, v37 offset1:1
	ds_write2_b32 v162, v38, v39 offset1:1
	ds_write2_b32 v163, v32, v33 offset1:1
	ds_write2_b32 v164, v34, v35 offset1:1
	ds_write2_b32 v165, v44, v45 offset1:1
	ds_write2_b32 v166, v46, v47 offset1:1
	ds_write2_b32 v167, v40, v41 offset1:1
	ds_write2_b32 v168, v42, v43 offset1:1
	ds_write2_b32 v169, v52, v53 offset1:1
	ds_write2_b32 v170, v54, v55 offset1:1
	ds_write2_b32 v171, v48, v49 offset1:1
	ds_write2_b32 v172, v50, v51 offset1:1
	ds_write2_b32 v173, v56, v57 offset1:1
	ds_write2_b32 v174, v58, v59 offset1:1
	ds_write2_b32 v175, v8, v9 offset1:1
	ds_write2_b32 v176, v10, v11 offset1:1
	ds_write2_b32 v177, v20, v21 offset1:1
	ds_write2_b32 v178, v22, v23 offset1:1
	ds_write2_b32 v179, v4, v5 offset1:1
	ds_write2_b32 v180, v6, v7 offset1:1
	ds_write2_b32 v181, v16, v17 offset1:1
	ds_write2_b32 v182, v18, v19 offset1:1
	ds_write2_b32 v183, v0, v1 offset1:1
	ds_write2_b32 v184, v2, v3 offset1:1
	ds_write2_b32 v185, v12, v13 offset1:1
	ds_write2_b32 v186, v14, v15 offset1:1
	ds_write2_b32 v187, v68, v69 offset1:1
	ds_write2_b32 v188, v70, v71 offset1:1
	s_waitcnt lgkmcnt(0)
	ds_read2_b32 v[136:137], v149 offset1:65
	v_add_u32_e32 v158, 0x400, v149
	s_lshl_b64 s[58:59], s[30:31], 1
	s_add_u32 s58, s40, s58
	s_addc_u32 s59, s41, s59
	ds_read2_b32 v[194:195], v149 offset0:130 offset1:195
	ds_read2_b32 v[196:197], v158 offset0:4 offset1:69
	ds_read2_b32 v[198:199], v158 offset0:134 offset1:199
	s_waitcnt lgkmcnt(0)
	v_mul_f32_e32 v136, v132, v136
	v_mul_f32_e32 v137, v133, v137
	v_cvt_pk_bf16_f32 v136, v136, v137
	v_lshl_add_u64 v[146:147], s[58:59], 0, v[144:145]
	s_waitcnt lgkmcnt(0)
	v_mul_f32_e32 v137, v134, v194
	v_mul_f32_e32 v138, v135, v195
	v_cvt_pk_bf16_f32 v137, v137, v138
	s_waitcnt lgkmcnt(0)
	v_mul_f32_e32 v138, v128, v196
	v_mul_f32_e32 v139, v129, v197
	v_cvt_pk_bf16_f32 v138, v138, v139
	s_waitcnt lgkmcnt(0)
	v_mul_f32_e32 v139, v130, v198
	v_mul_f32_e32 v189, v131, v199
	v_cvt_pk_bf16_f32 v139, v139, v189
	v_add_u32_e32 v189, s17, v148
	v_cmp_gt_i32_e32 vcc, s24, v189
	s_and_saveexec_b64 s[58:59], vcc
	v_ashrrev_i32_e32 v190, 7, v189
	v_mul_lo_u32 v190, v190, s29
	v_and_b32_e32 v189, 0x7f, v189
	v_add3_u32 v189, v189, s62, v190
	v_mad_u64_u32 v[190:191], s[60:61], v189, s25, 0
	v_ashrrev_i32_e32 v193, 31, v189
	v_mov_b32_e32 v192, v191
	v_mad_u64_u32 v[192:193], s[60:61], v193, s25, v[192:193]
	v_mov_b32_e32 v191, v192
	v_lshl_add_u64 v[190:191], v[190:191], 1, v[146:147]
	global_store_dwordx4 v[190:191], v[136:139], off nt
.Lha_39:
	s_or_b64 exec, exec, s[58:59]
	ds_read2_b32 v[136:137], v149 offset0:8 offset1:73
	v_add_u32_e32 v189, s17, v150
	v_cmp_gt_i32_e32 vcc, s24, v189
	ds_read2_b32 v[194:195], v149 offset0:138 offset1:203
	ds_read2_b32 v[196:197], v158 offset0:12 offset1:77
	ds_read2_b32 v[198:199], v158 offset0:142 offset1:207
	s_waitcnt lgkmcnt(0)
	v_mul_f32_e32 v136, v132, v136
	v_mul_f32_e32 v137, v133, v137
	v_cvt_pk_bf16_f32 v136, v136, v137
	s_waitcnt lgkmcnt(0)
	v_mul_f32_e32 v137, v134, v194
	v_mul_f32_e32 v138, v135, v195
	v_cvt_pk_bf16_f32 v137, v137, v138
	s_waitcnt lgkmcnt(0)
	v_mul_f32_e32 v138, v128, v196
	v_mul_f32_e32 v139, v129, v197
	v_cvt_pk_bf16_f32 v138, v138, v139
	s_waitcnt lgkmcnt(0)
	v_mul_f32_e32 v139, v130, v198
	v_mul_f32_e32 v190, v131, v199
	v_cvt_pk_bf16_f32 v139, v139, v190
	s_and_saveexec_b64 s[58:59], vcc
	v_ashrrev_i32_e32 v190, 7, v189
	v_mul_lo_u32 v190, v190, s29
	v_and_b32_e32 v189, 0x7f, v189
	v_add3_u32 v189, v189, s62, v190
	v_mad_u64_u32 v[190:191], s[60:61], v189, s25, 0
	v_ashrrev_i32_e32 v193, 31, v189
	v_mov_b32_e32 v192, v191
	v_mad_u64_u32 v[192:193], s[60:61], v193, s25, v[192:193]
	v_mov_b32_e32 v191, v192
	v_lshl_add_u64 v[190:191], v[190:191], 1, v[146:147]
	global_store_dwordx4 v[190:191], v[136:139], off nt
.Lha_41:
	s_or_b64 exec, exec, s[58:59]
	ds_read2_b32 v[136:137], v149 offset0:16 offset1:81
	v_add_u32_e32 v189, s17, v151
	v_cmp_gt_i32_e32 vcc, s24, v189
	ds_read2_b32 v[194:195], v149 offset0:146 offset1:211
	ds_read2_b32 v[196:197], v158 offset0:20 offset1:85
	ds_read2_b32 v[198:199], v158 offset0:150 offset1:215
	s_waitcnt lgkmcnt(0)
	v_mul_f32_e32 v136, v132, v136
	v_mul_f32_e32 v137, v133, v137
	v_cvt_pk_bf16_f32 v136, v136, v137
	s_waitcnt lgkmcnt(0)
	v_mul_f32_e32 v137, v134, v194
	v_mul_f32_e32 v138, v135, v195
	v_cvt_pk_bf16_f32 v137, v137, v138
	s_waitcnt lgkmcnt(0)
	v_mul_f32_e32 v138, v128, v196
	v_mul_f32_e32 v139, v129, v197
	v_cvt_pk_bf16_f32 v138, v138, v139
	s_waitcnt lgkmcnt(0)
	v_mul_f32_e32 v139, v130, v198
	v_mul_f32_e32 v190, v131, v199
	v_cvt_pk_bf16_f32 v139, v139, v190
	s_and_saveexec_b64 s[58:59], vcc
	v_ashrrev_i32_e32 v190, 7, v189
	v_mul_lo_u32 v190, v190, s29
	v_and_b32_e32 v189, 0x7f, v189
	v_add3_u32 v189, v189, s62, v190
	v_mad_u64_u32 v[190:191], s[60:61], v189, s25, 0
	v_ashrrev_i32_e32 v193, 31, v189
	v_mov_b32_e32 v192, v191
	v_mad_u64_u32 v[192:193], s[60:61], v193, s25, v[192:193]
	v_mov_b32_e32 v191, v192
	v_lshl_add_u64 v[190:191], v[190:191], 1, v[146:147]
	global_store_dwordx4 v[190:191], v[136:139], off nt
; #define LAS __attribute__((address_space(3)))
; __device__ __forceinline__ unsigned pk2(float lo, float hi) { return pg8::cvt_pk_bf16(lo, hi); }
; __device__ __forceinline__ void p0_finish(bf16* WT, const float* gain, int N, int k0, int n0, int ldw, int blk, int off, int lane, const f32x4 (&v)[16], LAS float* scr) {
;     ...
;     for (int jj = 0; jj < 8; ++jj) { const int n = (lane >> 3) + 8 * jj; const LAS float* s = scr + (8 * c8) * 65 + n;
;         u32x4 o; o.x = pk2(s[0 * 65] * g0[0], s[1 * 65] * g0[1]); o.y = pk2(s[2 * 65] * g0[2], s[3 * 65] * g0[3]); o.z = pk2(s[4 * 65] * g1[0], s[5 * 65] * g1[1]); o.w = pk2(s[6 * 65] * g1[2], s[7 * 65] * g1[3]);
;         const int ng = n0 + n;
;         if (ng < N) { const int row = (ng >> 7) * blk + (ng & 127) + off; __builtin_nontemporal_store(o, (u32x4*)(WT + (size_t)row * ldw + k0 + 8 * c8)); } }
.Lha_43:
	s_or_b64 exec, exec, s[58:59]
	ds_read2_b32 v[136:137], v149 offset0:24 offset1:89
	v_add_u32_e32 v189, s17, v152
	v_cmp_gt_i32_e32 vcc, s24, v189
	ds_read2_b32 v[194:195], v149 offset0:154 offset1:219
	ds_read2_b32 v[196:197], v158 offset0:28 offset1:93
	ds_read2_b32 v[198:199], v158 offset0:158 offset1:223
	s_waitcnt lgkmcnt(0)
	v_mul_f32_e32 v136, v132, v136
	v_mul_f32_e32 v137, v133, v137
	v_cvt_pk_bf16_f32 v136, v136, v137
	s_waitcnt lgkmcnt(0)
	v_mul_f32_e32 v137, v134, v194
	v_mul_f32_e32 v138, v135, v195
	v_cvt_pk_bf16_f32 v137, v137, v138
	s_waitcnt lgkmcnt(0)
	v_mul_f32_e32 v138, v128, v196
	v_mul_f32_e32 v139, v129, v197
	v_cvt_pk_bf16_f32 v138, v138, v139
	s_waitcnt lgkmcnt(0)
	v_mul_f32_e32 v139, v130, v198
	v_mul_f32_e32 v190, v131, v199
	v_cvt_pk_bf16_f32 v139, v139, v190
	s_and_saveexec_b64 s[58:59], vcc
	v_ashrrev_i32_e32 v190, 7, v189
	v_mul_lo_u32 v190, v190, s29
	v_and_b32_e32 v189, 0x7f, v189
	v_add3_u32 v189, v189, s62, v190
	v_mad_u64_u32 v[190:191], s[60:61], v189, s25, 0
	v_ashrrev_i32_e32 v193, 31, v189
	v_mov_b32_e32 v192, v191
	v_mad_u64_u32 v[192:193], s[60:61], v193, s25, v[192:193]
	v_mov_b32_e32 v191, v192
	v_lshl_add_u64 v[190:191], v[190:191], 1, v[146:147]
	global_store_dwordx4 v[190:191], v[136:139], off nt
.Lha_45:
	s_or_b64 exec, exec, s[58:59]
	ds_read2_b32 v[136:137], v149 offset0:32 offset1:97
	v_add_u32_e32 v189, s17, v153
	v_cmp_gt_i32_e32 vcc, s24, v189
	ds_read2_b32 v[194:195], v149 offset0:162 offset1:227
	ds_read2_b32 v[196:197], v158 offset0:36 offset1:101
	ds_read2_b32 v[198:199], v158 offset0:166 offset1:231
	s_waitcnt lgkmcnt(0)
	v_mul_f32_e32 v136, v132, v136
	v_mul_f32_e32 v137, v133, v137
	v_cvt_pk_bf16_f32 v136, v136, v137
	s_waitcnt lgkmcnt(0)
	v_mul_f32_e32 v137, v134, v194
	v_mul_f32_e32 v138, v135, v195
	v_cvt_pk_bf16_f32 v137, v137, v138
	s_waitcnt lgkmcnt(0)
	v_mul_f32_e32 v138, v128, v196
	v_mul_f32_e32 v139, v129, v197
	v_cvt_pk_bf16_f32 v138, v138, v139
	s_waitcnt lgkmcnt(0)
	v_mul_f32_e32 v139, v130, v198
	v_mul_f32_e32 v190, v131, v199
	v_cvt_pk_bf16_f32 v139, v139, v190
	s_and_saveexec_b64 s[58:59], vcc
	v_ashrrev_i32_e32 v190, 7, v189
	v_mul_lo_u32 v190, v190, s29
	v_and_b32_e32 v189, 0x7f, v189
	v_add3_u32 v189, v189, s62, v190
	v_mad_u64_u32 v[190:191], s[60:61], v189, s25, 0
	v_ashrrev_i32_e32 v193, 31, v189
	v_mov_b32_e32 v192, v191
	v_mad_u64_u32 v[192:193], s[60:61], v193, s25, v[192:193]
	v_mov_b32_e32 v191, v192
	v_lshl_add_u64 v[190:191], v[190:191], 1, v[146:147]
	global_store_dwordx4 v[190:191], v[136:139], off nt
.Lha_47:
	s_or_b64 exec, exec, s[58:59]
	ds_read2_b32 v[136:137], v149 offset0:40 offset1:105
	v_add_u32_e32 v189, s17, v154
	v_cmp_gt_i32_e32 vcc, s24, v189
	ds_read2_b32 v[194:195], v149 offset0:170 offset1:235
	ds_read2_b32 v[196:197], v158 offset0:44 offset1:109
	ds_read2_b32 v[198:199], v158 offset0:174 offset1:239
	s_waitcnt lgkmcnt(0)
	v_mul_f32_e32 v136, v132, v136
	v_mul_f32_e32 v137, v133, v137
	v_cvt_pk_bf16_f32 v136, v136, v137
	s_waitcnt lgkmcnt(0)
	v_mul_f32_e32 v137, v134, v194
	v_mul_f32_e32 v138, v135, v195
	v_cvt_pk_bf16_f32 v137, v137, v138
	s_waitcnt lgkmcnt(0)
	v_mul_f32_e32 v138, v128, v196
	v_mul_f32_e32 v139, v129, v197
	v_cvt_pk_bf16_f32 v138, v138, v139
	s_waitcnt lgkmcnt(0)
	v_mul_f32_e32 v139, v130, v198
	v_mul_f32_e32 v190, v131, v199
	v_cvt_pk_bf16_f32 v139, v139, v190
	s_and_saveexec_b64 s[58:59], vcc
	v_ashrrev_i32_e32 v190, 7, v189
	v_mul_lo_u32 v190, v190, s29
	v_and_b32_e32 v189, 0x7f, v189
	v_add3_u32 v189, v189, s62, v190
	v_mad_u64_u32 v[190:191], s[60:61], v189, s25, 0
	v_ashrrev_i32_e32 v193, 31, v189
	v_mov_b32_e32 v192, v191
	v_mad_u64_u32 v[192:193], s[60:61], v193, s25, v[192:193]
	v_mov_b32_e32 v191, v192
	v_lshl_add_u64 v[190:191], v[190:191], 1, v[146:147]
	global_store_dwordx4 v[190:191], v[136:139], off nt
.Lha_49:
	s_or_b64 exec, exec, s[58:59]
	ds_read2_b32 v[136:137], v149 offset0:48 offset1:113
	v_add_u32_e32 v189, s17, v155
	v_cmp_gt_i32_e32 vcc, s24, v189
	ds_read2_b32 v[194:195], v149 offset0:178 offset1:243
	ds_read2_b32 v[196:197], v158 offset0:52 offset1:117
	ds_read2_b32 v[198:199], v158 offset0:182 offset1:247
	s_waitcnt lgkmcnt(0)
	v_mul_f32_e32 v136, v132, v136
	v_mul_f32_e32 v137, v133, v137
	v_cvt_pk_bf16_f32 v136, v136, v137
	s_waitcnt lgkmcnt(0)
	v_mul_f32_e32 v137, v134, v194
	v_mul_f32_e32 v138, v135, v195
	v_cvt_pk_bf16_f32 v137, v137, v138
	s_waitcnt lgkmcnt(0)
	v_mul_f32_e32 v138, v128, v196
	v_mul_f32_e32 v139, v129, v197
	v_cvt_pk_bf16_f32 v138, v138, v139
	s_waitcnt lgkmcnt(0)
	v_mul_f32_e32 v139, v130, v198
	v_mul_f32_e32 v190, v131, v199
	v_cvt_pk_bf16_f32 v139, v139, v190
	s_and_saveexec_b64 s[58:59], vcc
	v_ashrrev_i32_e32 v190, 7, v189
	v_mul_lo_u32 v190, v190, s29
	v_and_b32_e32 v189, 0x7f, v189
	v_add3_u32 v189, v189, s62, v190
	v_mad_u64_u32 v[190:191], s[60:61], v189, s25, 0
	v_ashrrev_i32_e32 v193, 31, v189
	v_mov_b32_e32 v192, v191
	v_mad_u64_u32 v[192:193], s[60:61], v193, s25, v[192:193]
	v_mov_b32_e32 v191, v192
	v_lshl_add_u64 v[190:191], v[190:191], 1, v[146:147]
	global_store_dwordx4 v[190:191], v[136:139], off nt
.Lha_51:
	s_or_b64 exec, exec, s[58:59]
	ds_read2_b32 v[136:137], v149 offset0:56 offset1:121
	ds_read2_b32 v[194:195], v149 offset0:186 offset1:251
	ds_read2_b32 v[196:197], v158 offset0:60 offset1:125
	ds_read2_b32 v[198:199], v158 offset0:190 offset1:255
	s_waitcnt lgkmcnt(0)
	v_mul_f32_e32 v132, v132, v136
	v_mul_f32_e32 v133, v133, v137
	v_cvt_pk_bf16_f32 v132, v132, v133
	s_waitcnt lgkmcnt(0)
	v_mul_f32_e32 v133, v134, v194
	v_mul_f32_e32 v134, v135, v195
	v_cvt_pk_bf16_f32 v133, v133, v134
	s_waitcnt lgkmcnt(0)
	v_mul_f32_e32 v128, v128, v196
	v_mul_f32_e32 v129, v129, v197
	v_cvt_pk_bf16_f32 v134, v128, v129
	v_add_u32_e32 v128, s17, v157
	v_cmp_gt_i32_e32 vcc, s24, v128
	s_waitcnt lgkmcnt(0)
	v_mul_f32_e32 v129, v130, v198
	v_mul_f32_e32 v130, v131, v199
	v_cvt_pk_bf16_f32 v135, v129, v130
	s_and_saveexec_b64 s[58:59], vcc
	v_ashrrev_i32_e32 v129, 7, v128
	v_mul_lo_u32 v129, v129, s29
	v_and_b32_e32 v128, 0x7f, v128
	v_add3_u32 v128, v128, s62, v129
	v_ashrrev_i32_e32 v131, 31, v128
	v_mad_u64_u32 v[128:129], s[60:61], v128, s25, 0
	v_mov_b32_e32 v130, v129
	v_mad_u64_u32 v[130:131], s[60:61], v131, s25, v[130:131]
	v_mov_b32_e32 v129, v130
	v_lshl_add_u64 v[128:129], v[128:129], 1, v[146:147]
	global_store_dwordx4 v[128:129], v[132:135], off nt

; #define LAS __attribute__((address_space(3)))
; __device__ __forceinline__ unsigned pk2(float lo, float hi) { return pg8::cvt_pk_bf16(lo, hi); }
; __device__ __forceinline__ void p0_finish(bf16* WT, const float* gain, int N, int k0, int n0, int ldw, int blk, int off, int lane, const f32x4 (&v)[16], LAS float* scr) {
;     const int c = lane & 15, rq = lane >> 4, c8 = lane & 7;
;     f32x4 g0 = {1.f, 1.f, 1.f, 1.f}, g1 = g0;
;     if (gain) { g0 = *(const f32x4*)(gain + k0 + 8 * c8); g1 = *(const f32x4*)(gain + k0 + 8 * c8 + 4); }
; #pragma unroll
;     for (int j = 0; j < 16; ++j) { LAS float* s = scr + (4 * j + rq) * 65 + 4 * c; s[0] = v[j][0]; s[1] = v[j][1]; s[2] = v[j][2]; s[3] = v[j][3]; }
;     asm volatile("s_waitcnt lgkmcnt(0)" ::: "memory");
; #pragma unroll
;     for (int jj = 0; jj < 8; ++jj) { const int n = (lane >> 3) + 8 * jj; const LAS float* s = scr + (8 * c8) * 65 + n;
;         u32x4 o; o.x = pk2(s[0 * 65] * g0[0], s[1 * 65] * g0[1]); o.y = pk2(s[2 * 65] * g0[2], s[3 * 65] * g0[3]); o.z = pk2(s[4 * 65] * g1[0], s[5 * 65] * g1[1]); o.w = pk2(s[6 * 65] * g1[2], s[7 * 65] * g1[3]);
;         const int ng = n0 + n;
;         if (ng < N) { const int row = (ng >> 7) * blk + (ng & 127) + off; __builtin_nontemporal_store(o, (u32x4*)(WT + (size_t)row * ldw + k0 + 8 * c8)); } }
.Lha_p0w_b1:
	ds_write2_b32 v156, v64, v65 offset1:1
	ds_write2_b32 v156, v66, v67 offset0:2 offset1:3
	ds_write2_b32 v159, v60, v61 offset1:1
	ds_write2_b32 v160, v62, v63 offset1:1
	ds_write2_b32 v161, v76, v77 offset1:1
	ds_write2_b32 v162, v78, v79 offset1:1
	ds_write2_b32 v163, v72, v73 offset1:1
	ds_write2_b32 v164, v74, v75 offset1:1
	ds_write2_b32 v165, v84, v85 offset1:1
	ds_write2_b32 v166, v86, v87 offset1:1
	ds_write2_b32 v167, v80, v81 offset1:1
	ds_write2_b32 v168, v82, v83 offset1:1
	ds_write2_b32 v169, v92, v93 offset1:1
	ds_write2_b32 v170, v94, v95 offset1:1
	ds_write2_b32 v171, v88, v89 offset1:1
	ds_write2_b32 v172, v90, v91 offset1:1
	ds_write2_b32 v173, v100, v101 offset1:1
	ds_write2_b32 v174, v102, v103 offset1:1
	ds_write2_b32 v175, v96, v97 offset1:1
	ds_write2_b32 v176, v98, v99 offset1:1
	ds_write2_b32 v177, v108, v109 offset1:1
	ds_write2_b32 v178, v110, v111 offset1:1
	ds_write2_b32 v179, v104, v105 offset1:1
	ds_write2_b32 v180, v106, v107 offset1:1
	ds_write2_b32 v181, v116, v117 offset1:1
	ds_write2_b32 v182, v118, v119 offset1:1
	ds_write2_b32 v183, v112, v113 offset1:1
	ds_write2_b32 v184, v114, v115 offset1:1
	ds_write2_b32 v185, v124, v125 offset1:1
	ds_write2_b32 v186, v126, v127 offset1:1
	ds_write2_b32 v187, v120, v121 offset1:1
	ds_write2_b32 v188, v122, v123 offset1:1
	s_waitcnt lgkmcnt(0)
	ds_read2_b32 v[136:137], v149 offset1:65
	s_lshl_b64 s[58:59], s[52:53], 1
	s_add_u32 s58, s54, s58
	s_addc_u32 s59, s55, s59
	v_lshl_add_u64 v[146:147], s[58:59], 0, v[144:145]
	ds_read2_b32 v[194:195], v149 offset0:130 offset1:195
	ds_read2_b32 v[196:197], v158 offset0:4 offset1:69
	ds_read2_b32 v[198:199], v158 offset0:134 offset1:199
	s_waitcnt lgkmcnt(0)
	v_mul_f32_e32 v136, v232, v136
	v_mul_f32_e32 v137, v233, v137
	v_cvt_pk_bf16_f32 v136, v136, v137
	s_waitcnt lgkmcnt(0)
	v_mul_f32_e32 v137, v234, v194
	v_mul_f32_e32 v138, v235, v195
	v_cvt_pk_bf16_f32 v137, v137, v138
	s_waitcnt lgkmcnt(0)
	v_mul_f32_e32 v138, v228, v196
	v_mul_f32_e32 v139, v229, v197
	v_cvt_pk_bf16_f32 v138, v138, v139
	s_waitcnt lgkmcnt(0)
	v_mul_f32_e32 v139, v230, v198
	v_mul_f32_e32 v159, v231, v199
	v_cvt_pk_bf16_f32 v139, v139, v159
	v_add_u32_e32 v159, s68, v148
	v_cmp_gt_i32_e32 vcc, s69, v159
	s_and_saveexec_b64 s[58:59], vcc
	v_ashrrev_i32_e32 v160, 7, v159
	v_mul_lo_u32 v160, v160, s20
	v_and_b32_e32 v159, 0x7f, v159
	v_add3_u32 v159, v159, s71, v160
	v_mad_u64_u32 v[160:161], s[60:61], v159, s70, 0
	v_ashrrev_i32_e32 v163, 31, v159
	v_mov_b32_e32 v162, v161
	v_mad_u64_u32 v[162:163], s[60:61], v163, s70, v[162:163]
	v_mov_b32_e32 v161, v162
	v_lshl_add_u64 v[160:161], v[160:161], 1, v[146:147]
	global_store_dwordx4 v[160:161], v[136:139], off nt
.Lha_70:
	s_or_b64 exec, exec, s[58:59]
	ds_read2_b32 v[136:137], v149 offset0:8 offset1:73
	v_add_u32_e32 v159, s68, v150
	v_cmp_gt_i32_e32 vcc, s69, v159
	ds_read2_b32 v[194:195], v149 offset0:138 offset1:203
	ds_read2_b32 v[196:197], v158 offset0:12 offset1:77
	ds_read2_b32 v[198:199], v158 offset0:142 offset1:207
	s_waitcnt lgkmcnt(0)
	v_mul_f32_e32 v136, v232, v136
	v_mul_f32_e32 v137, v233, v137
	v_cvt_pk_bf16_f32 v136, v136, v137
	s_waitcnt lgkmcnt(0)
	v_mul_f32_e32 v137, v234, v194
	v_mul_f32_e32 v138, v235, v195
	v_cvt_pk_bf16_f32 v137, v137, v138
	s_waitcnt lgkmcnt(0)
	v_mul_f32_e32 v138, v228, v196
	v_mul_f32_e32 v139, v229, v197
	v_cvt_pk_bf16_f32 v138, v138, v139
	s_waitcnt lgkmcnt(0)
	v_mul_f32_e32 v139, v230, v198
	v_mul_f32_e32 v160, v231, v199
	v_cvt_pk_bf16_f32 v139, v139, v160
	s_and_saveexec_b64 s[58:59], vcc
	v_ashrrev_i32_e32 v160, 7, v159
	v_mul_lo_u32 v160, v160, s20
	v_and_b32_e32 v159, 0x7f, v159
	v_add3_u32 v159, v159, s71, v160
	v_mad_u64_u32 v[160:161], s[60:61], v159, s70, 0
	v_ashrrev_i32_e32 v163, 31, v159
	v_mov_b32_e32 v162, v161
	v_mad_u64_u32 v[162:163], s[60:61], v163, s70, v[162:163]
	v_mov_b32_e32 v161, v162
	v_lshl_add_u64 v[160:161], v[160:161], 1, v[146:147]
	global_store_dwordx4 v[160:161], v[136:139], off nt
.Lha_72:
	s_or_b64 exec, exec, s[58:59]
	ds_read2_b32 v[136:137], v149 offset0:16 offset1:81
	v_add_u32_e32 v159, s68, v151
	v_cmp_gt_i32_e32 vcc, s69, v159
	ds_read2_b32 v[194:195], v149 offset0:146 offset1:211
	ds_read2_b32 v[196:197], v158 offset0:20 offset1:85
	ds_read2_b32 v[198:199], v158 offset0:150 offset1:215
	s_waitcnt lgkmcnt(0)
	v_mul_f32_e32 v136, v232, v136
	v_mul_f32_e32 v137, v233, v137
	v_cvt_pk_bf16_f32 v136, v136, v137
	s_waitcnt lgkmcnt(0)
	v_mul_f32_e32 v137, v234, v194
	v_mul_f32_e32 v138, v235, v195
	v_cvt_pk_bf16_f32 v137, v137, v138
	s_waitcnt lgkmcnt(0)
	v_mul_f32_e32 v138, v228, v196
	v_mul_f32_e32 v139, v229, v197
	v_cvt_pk_bf16_f32 v138, v138, v139
	s_waitcnt lgkmcnt(0)
	v_mul_f32_e32 v139, v230, v198
	v_mul_f32_e32 v160, v231, v199
	v_cvt_pk_bf16_f32 v139, v139, v160
	s_and_saveexec_b64 s[58:59], vcc
	v_ashrrev_i32_e32 v160, 7, v159
	v_mul_lo_u32 v160, v160, s20
	v_and_b32_e32 v159, 0x7f, v159
	v_add3_u32 v159, v159, s71, v160
	v_mad_u64_u32 v[160:161], s[60:61], v159, s70, 0
	v_ashrrev_i32_e32 v163, 31, v159
	v_mov_b32_e32 v162, v161
	v_mad_u64_u32 v[162:163], s[60:61], v163, s70, v[162:163]
	v_mov_b32_e32 v161, v162
	v_lshl_add_u64 v[160:161], v[160:161], 1, v[146:147]
	global_store_dwordx4 v[160:161], v[136:139], off nt
; #define LAS __attribute__((address_space(3)))
; __device__ __forceinline__ unsigned pk2(float lo, float hi) { return pg8::cvt_pk_bf16(lo, hi); }
; __device__ __forceinline__ void p0_finish(bf16* WT, const float* gain, int N, int k0, int n0, int ldw, int blk, int off, int lane, const f32x4 (&v)[16], LAS float* scr) {
;     ...
;     for (int jj = 0; jj < 8; ++jj) { const int n = (lane >> 3) + 8 * jj; const LAS float* s = scr + (8 * c8) * 65 + n;
;         u32x4 o; o.x = pk2(s[0 * 65] * g0[0], s[1 * 65] * g0[1]); o.y = pk2(s[2 * 65] * g0[2], s[3 * 65] * g0[3]); o.z = pk2(s[4 * 65] * g1[0], s[5 * 65] * g1[1]); o.w = pk2(s[6 * 65] * g1[2], s[7 * 65] * g1[3]);
;         const int ng = n0 + n;
;         if (ng < N) { const int row = (ng >> 7) * blk + (ng & 127) + off; __builtin_nontemporal_store(o, (u32x4*)(WT + (size_t)row * ldw + k0 + 8 * c8)); } }
.Lha_74:
	s_or_b64 exec, exec, s[58:59]
	ds_read2_b32 v[136:137], v149 offset0:24 offset1:89
	v_add_u32_e32 v159, s68, v152
	v_cmp_gt_i32_e32 vcc, s69, v159
	ds_read2_b32 v[194:195], v149 offset0:154 offset1:219
	ds_read2_b32 v[196:197], v158 offset0:28 offset1:93
	ds_read2_b32 v[198:199], v158 offset0:158 offset1:223
	s_waitcnt lgkmcnt(0)
	v_mul_f32_e32 v136, v232, v136
	v_mul_f32_e32 v137, v233, v137
	v_cvt_pk_bf16_f32 v136, v136, v137
	s_waitcnt lgkmcnt(0)
	v_mul_f32_e32 v137, v234, v194
	v_mul_f32_e32 v138, v235, v195
	v_cvt_pk_bf16_f32 v137, v137, v138
	s_waitcnt lgkmcnt(0)
	v_mul_f32_e32 v138, v228, v196
	v_mul_f32_e32 v139, v229, v197
	v_cvt_pk_bf16_f32 v138, v138, v139
	s_waitcnt lgkmcnt(0)
	v_mul_f32_e32 v139, v230, v198
	v_mul_f32_e32 v160, v231, v199
	v_cvt_pk_bf16_f32 v139, v139, v160
	s_and_saveexec_b64 s[58:59], vcc
	v_ashrrev_i32_e32 v160, 7, v159
	v_mul_lo_u32 v160, v160, s20
	v_and_b32_e32 v159, 0x7f, v159
	v_add3_u32 v159, v159, s71, v160
	v_mad_u64_u32 v[160:161], s[60:61], v159, s70, 0
	v_ashrrev_i32_e32 v163, 31, v159
	v_mov_b32_e32 v162, v161
	v_mad_u64_u32 v[162:163], s[60:61], v163, s70, v[162:163]
	v_mov_b32_e32 v161, v162
	v_lshl_add_u64 v[160:161], v[160:161], 1, v[146:147]
	global_store_dwordx4 v[160:161], v[136:139], off nt
.Lha_76:
	s_or_b64 exec, exec, s[58:59]
	ds_read2_b32 v[136:137], v149 offset0:32 offset1:97
	v_add_u32_e32 v159, s68, v153
	v_cmp_gt_i32_e32 vcc, s69, v159
	ds_read2_b32 v[194:195], v149 offset0:162 offset1:227
	ds_read2_b32 v[196:197], v158 offset0:36 offset1:101
	ds_read2_b32 v[198:199], v158 offset0:166 offset1:231
	s_waitcnt lgkmcnt(0)
	v_mul_f32_e32 v136, v232, v136
	v_mul_f32_e32 v137, v233, v137
	v_cvt_pk_bf16_f32 v136, v136, v137
	s_waitcnt lgkmcnt(0)
	v_mul_f32_e32 v137, v234, v194
	v_mul_f32_e32 v138, v235, v195
	v_cvt_pk_bf16_f32 v137, v137, v138
	s_waitcnt lgkmcnt(0)
	v_mul_f32_e32 v138, v228, v196
	v_mul_f32_e32 v139, v229, v197
	v_cvt_pk_bf16_f32 v138, v138, v139
	s_waitcnt lgkmcnt(0)
	v_mul_f32_e32 v139, v230, v198
	v_mul_f32_e32 v160, v231, v199
	v_cvt_pk_bf16_f32 v139, v139, v160
	s_and_saveexec_b64 s[58:59], vcc
	v_ashrrev_i32_e32 v160, 7, v159
	v_mul_lo_u32 v160, v160, s20
	v_and_b32_e32 v159, 0x7f, v159
	v_add3_u32 v159, v159, s71, v160
	v_mad_u64_u32 v[160:161], s[60:61], v159, s70, 0
	v_ashrrev_i32_e32 v163, 31, v159
	v_mov_b32_e32 v162, v161
	v_mad_u64_u32 v[162:163], s[60:61], v163, s70, v[162:163]
	v_mov_b32_e32 v161, v162
	v_lshl_add_u64 v[160:161], v[160:161], 1, v[146:147]
	global_store_dwordx4 v[160:161], v[136:139], off nt
.Lha_78:
	s_or_b64 exec, exec, s[58:59]
	ds_read2_b32 v[136:137], v149 offset0:40 offset1:105
	v_add_u32_e32 v159, s68, v154
	v_cmp_gt_i32_e32 vcc, s69, v159
	ds_read2_b32 v[194:195], v149 offset0:170 offset1:235
	ds_read2_b32 v[196:197], v158 offset0:44 offset1:109
	ds_read2_b32 v[198:199], v158 offset0:174 offset1:239
	s_waitcnt lgkmcnt(0)
	v_mul_f32_e32 v136, v232, v136
	v_mul_f32_e32 v137, v233, v137
	v_cvt_pk_bf16_f32 v136, v136, v137
	s_waitcnt lgkmcnt(0)
	v_mul_f32_e32 v137, v234, v194
	v_mul_f32_e32 v138, v235, v195
	v_cvt_pk_bf16_f32 v137, v137, v138
	s_waitcnt lgkmcnt(0)
	v_mul_f32_e32 v138, v228, v196
	v_mul_f32_e32 v139, v229, v197
	v_cvt_pk_bf16_f32 v138, v138, v139
	s_waitcnt lgkmcnt(0)
	v_mul_f32_e32 v139, v230, v198
	v_mul_f32_e32 v160, v231, v199
	v_cvt_pk_bf16_f32 v139, v139, v160
	s_and_saveexec_b64 s[58:59], vcc
	v_ashrrev_i32_e32 v160, 7, v159
	v_mul_lo_u32 v160, v160, s20
	v_and_b32_e32 v159, 0x7f, v159
	v_add3_u32 v159, v159, s71, v160
	v_mad_u64_u32 v[160:161], s[60:61], v159, s70, 0
	v_ashrrev_i32_e32 v163, 31, v159
	v_mov_b32_e32 v162, v161
	v_mad_u64_u32 v[162:163], s[60:61], v163, s70, v[162:163]
	v_mov_b32_e32 v161, v162
	v_lshl_add_u64 v[160:161], v[160:161], 1, v[146:147]
	global_store_dwordx4 v[160:161], v[136:139], off nt
.Lha_80:
	s_or_b64 exec, exec, s[58:59]
	ds_read2_b32 v[136:137], v149 offset0:48 offset1:113
	v_add_u32_e32 v159, s68, v155
	v_cmp_gt_i32_e32 vcc, s69, v159
	ds_read2_b32 v[194:195], v149 offset0:178 offset1:243
	ds_read2_b32 v[196:197], v158 offset0:52 offset1:117
	ds_read2_b32 v[198:199], v158 offset0:182 offset1:247
	s_waitcnt lgkmcnt(0)
	v_mul_f32_e32 v136, v232, v136
	v_mul_f32_e32 v137, v233, v137
	v_cvt_pk_bf16_f32 v136, v136, v137
	s_waitcnt lgkmcnt(0)
	v_mul_f32_e32 v137, v234, v194
	v_mul_f32_e32 v138, v235, v195
	v_cvt_pk_bf16_f32 v137, v137, v138
	s_waitcnt lgkmcnt(0)
	v_mul_f32_e32 v138, v228, v196
	v_mul_f32_e32 v139, v229, v197
	v_cvt_pk_bf16_f32 v138, v138, v139
	s_waitcnt lgkmcnt(0)
	v_mul_f32_e32 v139, v230, v198
	v_mul_f32_e32 v160, v231, v199
	v_cvt_pk_bf16_f32 v139, v139, v160
	s_and_saveexec_b64 s[58:59], vcc
	v_ashrrev_i32_e32 v160, 7, v159
	v_mul_lo_u32 v160, v160, s20
	v_and_b32_e32 v159, 0x7f, v159
	v_add3_u32 v159, v159, s71, v160
	v_mad_u64_u32 v[160:161], s[60:61], v159, s70, 0
	v_ashrrev_i32_e32 v163, 31, v159
	v_mov_b32_e32 v162, v161
	v_mad_u64_u32 v[162:163], s[60:61], v163, s70, v[162:163]
	v_mov_b32_e32 v161, v162
	v_lshl_add_u64 v[160:161], v[160:161], 1, v[146:147]
	global_store_dwordx4 v[160:161], v[136:139], off nt
.Lha_82:
	s_or_b64 exec, exec, s[58:59]
	ds_read2_b32 v[136:137], v149 offset0:56 offset1:121
	ds_read2_b32 v[194:195], v149 offset0:186 offset1:251
	ds_read2_b32 v[196:197], v158 offset0:60 offset1:125
	ds_read2_b32 v[198:199], v158 offset0:190 offset1:255
	s_waitcnt lgkmcnt(0)
	v_mul_f32_e32 v232, v232, v136
	v_mul_f32_e32 v233, v233, v137
	v_cvt_pk_bf16_f32 v232, v232, v233
	s_waitcnt lgkmcnt(0)
	v_mul_f32_e32 v233, v234, v194
	v_mul_f32_e32 v234, v235, v195
	v_cvt_pk_bf16_f32 v233, v233, v234
	s_waitcnt lgkmcnt(0)
	v_mul_f32_e32 v228, v228, v196
	v_mul_f32_e32 v229, v229, v197
	v_cvt_pk_bf16_f32 v234, v228, v229
	v_add_u32_e32 v228, s68, v157
	v_cmp_gt_i32_e32 vcc, s69, v228
	s_waitcnt lgkmcnt(0)
	v_mul_f32_e32 v229, v230, v198
	v_mul_f32_e32 v230, v231, v199
	v_cvt_pk_bf16_f32 v235, v229, v230
	s_and_saveexec_b64 s[58:59], vcc
	v_ashrrev_i32_e32 v229, 7, v228
	v_mul_lo_u32 v229, v229, s20
	v_and_b32_e32 v228, 0x7f, v228
	v_add3_u32 v228, v228, s71, v229
	v_ashrrev_i32_e32 v231, 31, v228
	v_mad_u64_u32 v[228:229], s[60:61], v228, s70, 0
	v_mov_b32_e32 v230, v229
	v_mad_u64_u32 v[230:231], s[60:61], v231, s70, v[230:231]
	v_mov_b32_e32 v229, v230
	v_lshl_add_u64 v[228:229], v[228:229], 1, v[146:147]
	global_store_dwordx4 v[228:229], v[232:235], off nt
	s_branch .Lha_21

; __global__ void __launch_bounds__(NWAVES * 64, 2) fwd(Args args) {
;     ...
;           for (;;) {
;             __syncthreads();
;             if (tid == 0) MISC[16] = qpre;
;             __syncthreads();
;             constexpr int NB64 = (NCB * 3) / 4, NB16 = (NCB - NB64) * 4;
;             const unsigned q = MISC[16]; if (q >= 512u + (DEFER_AT == 5 ? (unsigned)(NB64 + NB16) : 0u)) break;
.LBB0_643:
	s_or_b64 exec, exec, s[2:3]
	s_waitcnt lgkmcnt(0)
	s_barrier
	ds_read_b32 v0, v164
	s_movk_i32 s2, 0x586
	s_waitcnt lgkmcnt(0)
	v_cmp_lt_u32_e64 s[2:3], s2, v0
	v_readfirstlane_b32 s25, v0
	s_and_b64 vcc, exec, s[2:3]
	s_cbranch_vccnz .LBB0_640
	s_and_saveexec_b64 s[6:7], s[4:5]
	s_cbranch_execz .LBB0_646
	v_mov_b32_e32 v0, v161
	s_nop 0
	v_ashrrev_i32_e32 v1, 31, v0
	v_lshl_add_u64 v[0:1], v[0:1], 2, s[44:45]
	global_atomic_add v162, v[0:1], v165, off sc0

; __global__ void __launch_bounds__(NWAVES * 64, 2) fwd(Args args) {
;     ...
;             if (!conv) attn_wg(PROJ, CONCAT, idx, L, tid, lane, wave);
;             else {
;                 const bool small = idx >= NB64; const int first = NI0 + (small ? NB64 * 64 + (idx - NB64) * 16 : idx * 64) + wave;
;                 f32x4 va[16], vb[16]; P0T_DECL(a); P0T_DECL(b);
.LBB0_679:
	s_and_b64 vcc, exec, s[4:5]
	s_cbranch_vccz .LBB0_640
	s_add_i32 s4, s25, 0xfffffe00
	s_lshl_b32 s58, s4, 4
	s_addk_i32 s58, 0x3c90
	s_lshl_b32 s42, s4, 6
	s_cmpk_gt_u32 s4, 0x142
	s_cselect_b32 s5, s58, s42
	s_add_i32 s25, s86, s5
	s_cmpk_lt_u32 s4, 0x143
	s_mov_b64 s[4:5], -1
	s_cbranch_scc0 .LBB0_882
	s_add_i32 s42, s42, s28
	s_cmpk_gt_u32 s42, 0xfff
	s_cbranch_scc0 .LBB0_685
	s_cmpk_gt_u32 s42, 0x65ff
	s_cbranch_scc0 .LBB0_942
	s_and_b32 s4, s42, 0x7ffffc0
	s_add_i32 s64, s4, 0xffff9a00
	s_mov_b64 s[70:71], 0
	s_cbranch_execz .LBB0_943

.LBB0_1140:
	s_cmpk_lt_u32 s8, 0xc0
	s_cbranch_scc1 .Lhb_done
	v_writelane_b32 v238, s0, 0
	v_writelane_b32 v238, s1, 1
	v_writelane_b32 v238, s2, 2
	v_writelane_b32 v238, s3, 3
	v_writelane_b32 v238, s4, 4
	v_writelane_b32 v238, s5, 5
	v_writelane_b32 v238, s6, 6
	v_writelane_b32 v238, s7, 7
	v_writelane_b32 v238, s8, 8
	v_writelane_b32 v238, s9, 9
	v_writelane_b32 v238, s10, 10
	v_writelane_b32 v238, s11, 11
	v_writelane_b32 v238, s12, 12
	v_writelane_b32 v238, s13, 13
	v_writelane_b32 v238, s14, 14
	v_writelane_b32 v238, s15, 15
	v_writelane_b32 v238, s16, 16
	v_writelane_b32 v238, s17, 17
	v_writelane_b32 v238, s18, 18
	v_writelane_b32 v238, s19, 19
	v_writelane_b32 v238, s20, 20
	v_writelane_b32 v238, s21, 21
	v_writelane_b32 v238, s22, 22
	v_writelane_b32 v238, s23, 23
	v_writelane_b32 v238, s24, 24
	v_writelane_b32 v238, s25, 25
	v_writelane_b32 v238, s26, 26
	v_writelane_b32 v238, s27, 27
	v_writelane_b32 v238, s28, 28
	v_writelane_b32 v238, s29, 29
	v_writelane_b32 v238, s30, 30
	v_writelane_b32 v238, s31, 31
	v_writelane_b32 v238, s32, 32
	v_writelane_b32 v238, s33, 33
	v_writelane_b32 v238, s34, 34
	v_writelane_b32 v238, s35, 35
	v_writelane_b32 v238, s36, 36
	v_writelane_b32 v238, s37, 37
	v_writelane_b32 v238, s38, 38
	v_writelane_b32 v238, s39, 39
	v_writelane_b32 v238, s40, 40
	v_writelane_b32 v238, s41, 41
	v_writelane_b32 v238, s42, 42
	v_writelane_b32 v238, s43, 43
	v_writelane_b32 v238, s44, 44
	v_writelane_b32 v238, s45, 45
	v_writelane_b32 v238, s46, 46
	v_writelane_b32 v238, s47, 47
	v_writelane_b32 v238, s48, 48
	v_writelane_b32 v238, s49, 49
	v_writelane_b32 v238, s50, 50
	v_writelane_b32 v238, s51, 51
	v_writelane_b32 v238, s52, 52
	v_writelane_b32 v238, s53, 53
	v_writelane_b32 v238, s54, 54
	v_writelane_b32 v238, s55, 55
	v_writelane_b32 v238, s56, 56
	v_writelane_b32 v238, s57, 57
	v_writelane_b32 v238, s58, 58
	v_writelane_b32 v238, s59, 59
	v_writelane_b32 v238, s60, 60
	v_writelane_b32 v238, s61, 61
	v_writelane_b32 v238, s62, 62
	v_writelane_b32 v238, s63, 63
	v_writelane_b32 v239, s64, 0
	v_writelane_b32 v239, s65, 1
	v_writelane_b32 v239, s66, 2
	v_writelane_b32 v239, s67, 3
	v_writelane_b32 v239, s68, 4
	v_writelane_b32 v239, s69, 5
	v_writelane_b32 v239, s70, 6
	v_writelane_b32 v239, s71, 7
	v_writelane_b32 v239, s72, 8
	v_writelane_b32 v239, s73, 9
	v_writelane_b32 v239, s74, 10
	v_writelane_b32 v239, s75, 11
	v_writelane_b32 v239, s76, 12
	v_writelane_b32 v239, s77, 13
	v_writelane_b32 v239, s78, 14
	v_writelane_b32 v239, s79, 15
	v_writelane_b32 v239, s80, 16
	v_writelane_b32 v239, s81, 17
	v_writelane_b32 v239, s82, 18
	v_writelane_b32 v239, s83, 19
	v_writelane_b32 v239, s84, 20
	v_writelane_b32 v239, s85, 21
	v_writelane_b32 v239, s86, 22
	v_writelane_b32 v239, s87, 23
	v_writelane_b32 v239, s88, 24
	v_writelane_b32 v239, s89, 25
	v_writelane_b32 v239, s90, 26
	v_writelane_b32 v239, s91, 27
	v_writelane_b32 v239, s92, 28
	v_writelane_b32 v239, s93, 29
	v_writelane_b32 v239, s94, 30
	v_writelane_b32 v239, s95, 31
	v_writelane_b32 v239, s96, 32
	v_writelane_b32 v239, s97, 33
	v_writelane_b32 v239, s98, 34
	v_writelane_b32 v239, s99, 35
	v_writelane_b32 v239, s100, 36
	v_writelane_b32 v239, s101, 37
	v_writelane_b32 v239, vcc_lo, 38
	v_writelane_b32 v239, vcc_hi, 39
	v_writelane_b32 v239, m0, 40
	s_add_i32 s75, s8, 0xffffff40
	s_mov_b32 s33, 64
	s_lshl_b32 s9, s28, 6
	s_lshl_b32 s4, s75, 3
	s_add_i32 s16, s4, s28
	s_lshl_b32 s18, s33, 3
	s_add_u32 s6, s14, 0x40000
	s_addc_u32 s7, s15, 0
	s_add_u32 s36, s14, 0x400000
	s_addc_u32 s37, s15, 0
	s_add_u32 s34, s14, 0xb400000
	s_addc_u32 s35, s15, 0
	s_load_dwordx2 s[96:97], s[0:1], 0x98
	s_add_u32 s10, s14, 0x10c00000
	s_addc_u32 s11, s15, 0
	s_add_u32 s26, s14, 0x2a800000
	s_addc_u32 s27, s15, 0
	s_waitcnt lgkmcnt(0)
	s_cmp_lt_i32 s96, 1
	s_cselect_b64 s[4:5], -1, 0
	s_cmp_gt_i32 s97, 0
	s_cselect_b64 s[20:21], -1, 0
	s_and_b64 s[4:5], s[4:5], s[20:21]
	s_and_b64 vcc, exec, s[4:5]
	s_mul_i32 s74, s28, 0x4100
	s_cbranch_vccz .Lhb_end
	s_abs_i32 s4, s18
	v_cvt_f32_u32_e32 v0, s4
	s_sub_i32 s5, 0, s4
	s_add_i32 s19, s74, 0
	v_mbcnt_lo_u32_b32 v140, -1, 0
	v_mbcnt_hi_u32_b32 v140, -1, v140
	v_rcp_iflag_f32_e32 v0, v0
	s_nop 0
	v_mul_f32_e32 v0, 0x4f7ffffe, v0
	v_cvt_u32_f32_e32 v0, v0
	s_nop 0
	v_readfirstlane_b32 s17, v0
	s_mul_i32 s5, s5, s17
	s_mul_hi_u32 s5, s17, s5
	s_add_i32 s17, s17, s5
	s_mul_hi_u32 s5, s17, 0x9c4e
	s_mul_i32 s5, s5, s4
	s_sub_i32 s5, 0x9c4e, s5
	s_sub_i32 s17, s5, s4
	s_cmp_ge_u32 s5, s4
	s_cselect_b32 s5, s17, s5
	s_sub_i32 s17, s5, s4
	s_cmp_ge_u32 s5, s4
	s_cselect_b32 s23, s17, s5
	s_sub_i32 s22, 0x9c4e, s23
	s_add_i32 s16, s16, 0x6500
	s_mov_b32 s22, 0x8100
	s_add_u32 s0, s0, 88
	s_addc_u32 s1, s1, 0
	s_add_u32 s34, s14, 0x25000000
	s_addc_u32 s35, s15, 0
	s_cmp_ge_i32 s16, s22
	s_cbranch_scc1 .Lhb_end
	s_cmpk_gt_i32 s16, 0x55ff
	s_cbranch_scc0 .Lhb_14
	s_cmpk_gt_u32 s16, 0x80ff
	s_cbranch_scc0 .Lhb_15
	s_add_u32 s42, s0, 48
	s_addc_u32 s43, s1, 0
	s_add_i32 s17, s16, 0x7f00
	s_and_b32 s20, s17, 0xffff
	s_mul_i32 s20, s20, 0x91a3
	s_load_dwordx2 s[4:5], s[0:1], 0x28
	s_lshr_b32 s20, s20, 23
	s_lshl_b32 s30, s20, 6
	s_mulk_i32 s20, 0xe1
	s_sub_i32 s17, s17, s20
	s_lshl_b32 s17, s17, 6
	s_and_b32 s17, s17, 0xffc0
	s_cbranch_execz .Lhb_16
	s_movk_i32 s25, 0x1040
	s_movk_i32 s24, 0x3820
	s_mov_b64 s[40:41], s[10:11]
	s_branch .Lhb_17
